# grid barrier: every workgroup polls the top counter directly (per-XCD generation stage removed) and the L1 invalidate is issued before the poll so it completes during the wait
# speedup vs baseline: 1.0321x; 1.0228x over previous
.LBB0_579:
	v_readlane_b32 s12, v253, 46
	v_readlane_b32 s13, v253, 47
	v_readlane_b32 s14, v253, 50
	v_readlane_b32 s15, v253, 51
	v_mov_b32_e32 v1, 0
	v_mov_b32_e32 v6, 1
	s_waitcnt lgkmcnt(0)
	s_nop 4
	global_atomic_add v6, v1, v6, s[12:13] sc0
	v_cvt_f32_u32_e32 v5, v3
	v_sub_u32_e32 v4, 0, v3
	v_rcp_iflag_f32_e32 v5, v5
	s_nop 1
	v_mul_f32_e32 v5, 0x4f7ffffe, v5
	v_cvt_u32_f32_e32 v5, v5
	v_mul_lo_u32 v0, v4, v5
	v_mul_hi_u32 v0, v5, v0
	v_add_u32_e32 v0, v5, v0
	s_waitcnt vmcnt(0)
	v_mul_hi_u32 v0, v6, v0
	v_mul_lo_u32 v4, v0, v3
	v_sub_u32_e32 v4, v6, v4
	v_add_u32_e32 v5, 1, v0
	v_cmp_ge_u32_e32 vcc, v4, v3
	s_nop 1
	v_cndmask_b32_e32 v0, v0, v5, vcc
	v_sub_u32_e32 v5, v4, v3
	v_cndmask_b32_e32 v4, v4, v5, vcc
	v_add_u32_e32 v5, 1, v0
	v_cmp_ge_u32_e32 vcc, v4, v3
	s_nop 1
	v_cndmask_b32_e32 v0, v0, v5, vcc
	v_add_u32_e32 v0, 1, v0
	v_mul_lo_u32 v4, v0, v3
	v_mul_lo_u32 v5, v0, v2
	v_add_u32_e32 v6, 1, v6
	v_cmp_ne_u32_e32 vcc, v6, v4
	s_mov_b32 s16, 0
	s_cbranch_vccnz .Lxb_wait
	buffer_wbl2 sc1
	buffer_inv sc1
	s_waitcnt vmcnt(0)
	v_mov_b32_e32 v4, 1
	global_atomic_add v1, v4, s[14:15]
	s_branch .Lxb_poll

.Lxb_poll:
	global_load_dword v4, v1, s[14:15] sc1
	s_waitcnt vmcnt(0)
	v_cmp_lt_u32_e32 vcc, v4, v5
	s_cbranch_vccz .Lxb_done
	s_add_i32 s16, s16, 1
	s_cmp_lt_u32 s16, 0x40000
	s_cbranch_scc0 .Lxb_done
	s_sleep 1
	s_branch .Lxb_poll
.Lxb_done:
	s_mov_b64 s[12:13], exec
	s_getpc_b64 s[98:99]
